# K=4096 GEMM loop counted vmcnt (no drain), Griffin carry chain de-serialised, HGRN waves s_setprio 3
# speedup vs baseline: 1.1388x; 1.0106x over previous
.LBB0_167:
	s_setprio 0
	s_mov_b64 s[42:43], 0

.LBB0_173:
	s_or_b64 exec, exec, s[42:43]
	s_waitcnt lgkmcnt(0)
	s_barrier
	ds_read_b32 v2, v126
	s_mov_b64 s[42:43], -1
	s_waitcnt lgkmcnt(0)
	v_cmp_lt_i32_e32 vcc, 31, v2
	v_readfirstlane_b32 s45, v2
	s_cbranch_vccnz .LBB0_168
	s_setprio 3
	v_readfirstlane_b32 s44, v147
	s_lshr_b32 s44, s44, 1
	s_ashr_i32 s42, s45, 2
	s_and_b32 s44, s44, 0x7fffffe0
	s_ashr_i32 s43, s42, 31
	v_or_b32_e32 v2, s44, v149
	v_cmp_lt_i32_e32 vcc, v166, v167
	s_and_b32 s45, s45, 3
	v_mul_lo_u32 v2, v2, s3
	v_cndmask_b32_e32 v3, v165, v166, vcc
	v_cmp_lt_i32_e32 vcc, v168, v167
	s_lshl_b64 s[46:47], s[42:43], 22
	s_lshl_b32 s51, s45, 8
	s_lshl_b64 s[42:43], s[42:43], 23
	s_lshl_b32 s45, s45, 9
	v_or_b32_e32 v170, v153, v2
	v_mov_b32_e32 v2, 0
	v_lshlrev_b32_e32 v172, 2, v3
	v_cndmask_b32_e32 v3, v165, v168, vcc
	s_or_b32 s46, s46, s51
	s_or_b32 s76, s42, s45
	s_mov_b32 s77, s43
	s_or_b32 s42, s42, s51
	v_lshl_add_u32 v171, s44, 2, v156
	s_mov_b32 s44, 64
	v_lshlrev_b32_e32 v173, 2, v3
	v_lshl_add_u64 v[138:139], s[46:47], 0, v[130:131]
	v_lshl_add_u64 v[140:141], s[76:77], 0, v[132:133]
	v_lshl_add_u64 v[142:143], s[46:47], 0, v[134:135]
	v_lshl_add_u64 v[144:145], s[42:43], 0, v[136:137]
	v_add_u32_e32 v174, v170, v153
	v_mov_b32_e32 v3, v2
	v_mov_b32_e32 v4, v2
	v_mov_b32_e32 v5, v2
	v_mov_b32_e32 v6, v2
	v_mov_b32_e32 v7, v2
	v_mov_b32_e32 v8, v2
	v_mov_b32_e32 v9, v2
	v_mov_b32_e32 v10, v2
	v_mov_b32_e32 v11, v2
	v_mov_b32_e32 v12, v2
	v_mov_b32_e32 v13, v2
	v_mov_b32_e32 v14, v2
	v_mov_b32_e32 v15, v2
	v_mov_b32_e32 v16, v2
	v_mov_b32_e32 v17, v2
	v_mov_b32_e32 v18, v2
	v_mov_b32_e32 v19, v2
	v_mov_b32_e32 v20, v2
	v_mov_b32_e32 v21, v2
	v_mov_b32_e32 v22, v2
	v_mov_b32_e32 v23, v2
	v_mov_b32_e32 v24, v2
	v_mov_b32_e32 v25, v2
	v_mov_b32_e32 v26, v2
	v_mov_b32_e32 v27, v2
	v_mov_b32_e32 v28, v2
	v_mov_b32_e32 v29, v2
	v_mov_b32_e32 v30, v2
	v_mov_b32_e32 v31, v2
	v_mov_b32_e32 v32, v2
	v_mov_b32_e32 v33, v2
	v_mov_b32_e32 v34, v2
	v_mov_b32_e32 v35, v2
	v_mov_b32_e32 v36, v2
	v_mov_b32_e32 v37, v2
	v_mov_b32_e32 v38, v2
	v_mov_b32_e32 v39, v2
	v_mov_b32_e32 v40, v2
	v_mov_b32_e32 v41, v2
	v_mov_b32_e32 v42, v2
	v_mov_b32_e32 v43, v2
	v_mov_b32_e32 v44, v2
	v_mov_b32_e32 v45, v2
	v_mov_b32_e32 v46, v2
	v_mov_b32_e32 v47, v2
	v_mov_b32_e32 v48, v2
	v_mov_b32_e32 v49, v2
	v_mov_b32_e32 v50, v2
	v_mov_b32_e32 v51, v2
	v_mov_b32_e32 v52, v2
	v_mov_b32_e32 v53, v2
	v_mov_b32_e32 v54, v2
	v_mov_b32_e32 v55, v2
	v_mov_b32_e32 v56, v2
	v_mov_b32_e32 v57, v2
	v_mov_b32_e32 v58, v2
	v_mov_b32_e32 v59, v2
	v_mov_b32_e32 v60, v2
	v_mov_b32_e32 v61, v2
	v_mov_b32_e32 v62, v2
	v_mov_b32_e32 v63, v2
	v_mov_b32_e32 v64, v2
	v_mov_b32_e32 v65, v2
	s_branch .LBB0_176

.LBB0_361:
	ds_read_b128 v[162:165], v130
	ds_read_b128 v[166:169], v131 offset:36864
	ds_read_b128 v[170:173], v130 offset:32
	ds_read_b128 v[174:177], v131 offset:36896
	ds_read_b128 v[178:181], v131 offset:41472
	ds_read_b128 v[182:185], v131 offset:41504
	s_cmp_gt_u32 s12, 60
	s_waitcnt lgkmcnt(4)
	v_mfma_f32_32x32x16_bf16 v[50:65], v[162:165], v[166:169], v[50:65]
	s_waitcnt lgkmcnt(1)
	v_mfma_f32_32x32x16_bf16 v[34:49], v[162:165], v[178:181], v[34:49]
	ds_read_b128 v[162:165], v130 offset:4608
	ds_read_b128 v[186:189], v130 offset:4640
	s_waitcnt lgkmcnt(1)
	v_mfma_f32_32x32x16_bf16 v[18:33], v[162:165], v[166:169], v[18:33]
	v_mfma_f32_32x32x16_bf16 v[2:17], v[162:165], v[178:181], v[2:17]
	v_mfma_f32_32x32x16_bf16 v[50:65], v[170:173], v[174:177], v[50:65]
	v_mfma_f32_32x32x16_bf16 v[34:49], v[170:173], v[182:185], v[34:49]
	s_waitcnt lgkmcnt(0)
	v_mfma_f32_32x32x16_bf16 v[18:33], v[186:189], v[174:177], v[18:33]
	ds_read_b128 v[162:165], v130 offset:64
	ds_read_b128 v[166:169], v131 offset:36928
	ds_read_b128 v[170:173], v130 offset:96
	ds_read_b128 v[174:177], v131 offset:36960
	v_mfma_f32_32x32x16_bf16 v[2:17], v[186:189], v[182:185], v[2:17]
	ds_read_b128 v[178:181], v131 offset:41536
	ds_read_b128 v[182:185], v131 offset:41568
	s_waitcnt lgkmcnt(4)
	v_mfma_f32_32x32x16_bf16 v[50:65], v[162:165], v[166:169], v[50:65]
	s_waitcnt lgkmcnt(1)
	v_mfma_f32_32x32x16_bf16 v[34:49], v[162:165], v[178:181], v[34:49]
	ds_read_b128 v[162:165], v130 offset:4672
	ds_read_b128 v[186:189], v130 offset:4704
	s_mov_b64 vcc, s[18:19]
	s_cbranch_vccnz .Lk5_last
	s_waitcnt vmcnt(8)
	ds_write_b128 v150, v[90:93] offset:18432
	ds_write_b128 v150, v[94:97] offset:23040
	ds_write_b128 v150, v[102:105] offset:27648
	ds_write_b128 v150, v[106:109] offset:32256
	ds_write_b128 v150, v[114:117] offset:55296
	ds_write_b128 v150, v[118:121] offset:59904
	ds_write_b128 v150, v[122:125] offset:64512
	ds_write_b128 v151, v[126:129] offset:32256
	s_branch .Lk5_join
.Lk5_last:
	s_waitcnt vmcnt(0)
	ds_write_b128 v150, v[90:93] offset:18432
	ds_write_b128 v150, v[94:97] offset:23040
	ds_write_b128 v150, v[102:105] offset:27648
	ds_write_b128 v150, v[106:109] offset:32256
	ds_write_b128 v150, v[114:117] offset:55296
	ds_write_b128 v150, v[118:121] offset:59904
	ds_write_b128 v150, v[122:125] offset:64512
	ds_write_b128 v151, v[126:129] offset:32256
.Lk5_join:
	s_waitcnt lgkmcnt(0)
	s_barrier
	v_mfma_f32_32x32x16_bf16 v[18:33], v[162:165], v[166:169], v[18:33]
	v_mfma_f32_32x32x16_bf16 v[2:17], v[162:165], v[178:181], v[2:17]
	v_mfma_f32_32x32x16_bf16 v[50:65], v[170:173], v[174:177], v[50:65]
	v_mfma_f32_32x32x16_bf16 v[34:49], v[170:173], v[182:185], v[34:49]
	v_mfma_f32_32x32x16_bf16 v[18:33], v[186:189], v[174:177], v[18:33]
	v_mfma_f32_32x32x16_bf16 v[2:17], v[186:189], v[182:185], v[2:17]
	s_cbranch_scc1 .LBB0_363
	v_add_co_u32_e32 v90, vcc, 0xb6c0000, v148
	s_nop 1
	v_addc_co_u32_e32 v91, vcc, 0, v149, vcc
	v_add_co_u32_e32 v94, vcc, 0xb700000, v148
	s_nop 1
	v_addc_co_u32_e32 v95, vcc, 0, v149, vcc
	v_add_co_u32_e32 v102, vcc, 0xb740000, v148
	global_load_dwordx4 v[90:93], v[90:91], off offset:640
	s_nop 0
	global_load_dwordx4 v[94:97], v[94:95], off offset:640
	v_addc_co_u32_e32 v103, vcc, 0, v149, vcc
	v_add_co_u32_e32 v106, vcc, 0xb780000, v148
	s_nop 1
	v_addc_co_u32_e32 v107, vcc, 0, v149, vcc
	v_add_co_u32_e32 v114, vcc, 0x10c0000, v146
	global_load_dwordx4 v[102:105], v[102:103], off offset:640
	s_nop 0
	global_load_dwordx4 v[106:109], v[106:107], off offset:640
	v_addc_co_u32_e32 v115, vcc, 0, v147, vcc
	v_add_co_u32_e32 v118, vcc, 0x1100000, v146
	s_nop 1
	v_addc_co_u32_e32 v119, vcc, 0, v147, vcc
	v_add_co_u32_e32 v122, vcc, 0x1140000, v146
	global_load_dwordx4 v[114:117], v[114:115], off offset:384
	s_nop 0
	global_load_dwordx4 v[118:121], v[118:119], off offset:384
	v_addc_co_u32_e32 v123, vcc, 0, v147, vcc
	v_add_co_u32_e32 v126, vcc, 0x1180000, v146
	s_nop 1
	v_addc_co_u32_e32 v127, vcc, 0, v147, vcc
	global_load_dwordx4 v[122:125], v[122:123], off offset:384
	s_nop 0
	global_load_dwordx4 v[126:129], v[126:127], off offset:384
.LBB0_363:
	ds_read_b128 v[146:149], v130 offset:18432
	ds_read_b128 v[162:165], v131 offset:55296
	ds_read_b128 v[166:169], v130 offset:18464
	ds_read_b128 v[170:173], v131 offset:55328
	ds_read_b128 v[174:177], v131 offset:59904
	ds_read_b128 v[178:181], v131 offset:59936
	s_andn2_b64 vcc, exec, s[20:21]
	s_waitcnt lgkmcnt(4)
	v_mfma_f32_32x32x16_bf16 v[50:65], v[146:149], v[162:165], v[50:65]
	s_waitcnt lgkmcnt(1)
	v_mfma_f32_32x32x16_bf16 v[34:49], v[146:149], v[174:177], v[34:49]
	ds_read_b128 v[146:149], v130 offset:23040
	ds_read_b128 v[182:185], v130 offset:23072
	s_waitcnt lgkmcnt(1)
	v_mfma_f32_32x32x16_bf16 v[18:33], v[146:149], v[162:165], v[18:33]
	v_mfma_f32_32x32x16_bf16 v[2:17], v[146:149], v[174:177], v[2:17]
	v_mfma_f32_32x32x16_bf16 v[50:65], v[166:169], v[170:173], v[50:65]
	v_mfma_f32_32x32x16_bf16 v[34:49], v[166:169], v[178:181], v[34:49]
	s_waitcnt lgkmcnt(0)
	v_mfma_f32_32x32x16_bf16 v[18:33], v[182:185], v[170:173], v[18:33]
	ds_read_b128 v[146:149], v130 offset:18496
	ds_read_b128 v[162:165], v131 offset:55360
	ds_read_b128 v[166:169], v130 offset:18528
	ds_read_b128 v[170:173], v131 offset:55392
	v_mfma_f32_32x32x16_bf16 v[2:17], v[182:185], v[178:181], v[2:17]
	ds_read_b128 v[174:177], v131 offset:59968
	ds_read_b128 v[178:181], v131 offset:60000
	s_waitcnt lgkmcnt(4)
	v_mfma_f32_32x32x16_bf16 v[50:65], v[146:149], v[162:165], v[50:65]
	s_waitcnt lgkmcnt(1)
	v_mfma_f32_32x32x16_bf16 v[34:49], v[146:149], v[174:177], v[34:49]
	ds_read_b128 v[146:149], v130 offset:23104
	ds_read_b128 v[182:185], v130 offset:23136
	s_waitcnt lgkmcnt(1)
	v_mfma_f32_32x32x16_bf16 v[18:33], v[146:149], v[162:165], v[18:33]
	v_mfma_f32_32x32x16_bf16 v[2:17], v[146:149], v[174:177], v[2:17]
	v_mfma_f32_32x32x16_bf16 v[50:65], v[166:169], v[170:173], v[50:65]
	v_mfma_f32_32x32x16_bf16 v[34:49], v[166:169], v[178:181], v[34:49]
	s_waitcnt lgkmcnt(0)
	v_mfma_f32_32x32x16_bf16 v[18:33], v[182:185], v[170:173], v[18:33]
	v_mfma_f32_32x32x16_bf16 v[2:17], v[182:185], v[178:181], v[2:17]
	s_cbranch_vccnz .LBB0_358
	s_waitcnt vmcnt(8)
	ds_write_b128 v150, v[66:69]
	ds_write_b128 v150, v[70:73] offset:4608
	ds_write_b128 v150, v[74:77] offset:9216
	ds_write_b128 v150, v[78:81] offset:13824
	ds_write_b128 v150, v[82:85] offset:36864
	ds_write_b128 v150, v[86:89] offset:41472
	ds_write_b128 v150, v[98:101] offset:46080
	ds_write_b128 v150, v[110:113] offset:50688
	s_branch .LBB0_358

.LBB0_523:
	s_or_b64 exec, exec, s[28:29]
	s_waitcnt lgkmcnt(0)
	ds_read_b128 v[66:69], v148 offset:33424
	ds_read_b128 v[72:75], v237 offset:42640
	ds_read_b128 v[76:79], v148 offset:33488
	ds_read_b128 v[80:83], v237 offset:42704
	ds_read_b128 v[84:87], v237 offset:44944
	ds_read_b128 v[88:91], v237 offset:45008
	s_waitcnt lgkmcnt(4)
	v_mfma_f32_16x16x32_bf16 v[72:75], v[66:69], v[72:75], 0
	s_waitcnt lgkmcnt(1)
	v_mfma_f32_16x16x32_bf16 v[66:69], v[66:69], v[84:87], 0
	v_add_u32_e32 v84, 0x5000, v155
	v_mfma_f32_16x16x32_bf16 v[72:75], v[76:79], v[80:83], v[72:75]
	v_lshlrev_b32_e32 v80, 4, v71
	v_mad_u64_u32 v[82:83], s[28:29], v70, s44, v[80:81]
	s_waitcnt lgkmcnt(0)
	v_mfma_f32_16x16x32_bf16 v[66:69], v[76:79], v[88:91], v[66:69]
	s_nop 7
	ds_write2_b32 v84, v72, v66 offset0:32 offset1:48
	ds_write2_b32 v84, v73, v67 offset0:65 offset1:81
	ds_write2_b32 v84, v74, v68 offset0:98 offset1:114
	ds_write2_b32 v84, v75, v69 offset0:131 offset1:147
	s_waitcnt lgkmcnt(0)
	ds_read_b32 v78, v80 offset:9600
	v_add_u32_e32 v68, 0x5080, v82
	v_add_u32_e32 v71, 0x50c0, v82
	v_mad_u64_u32 v[66:67], s[28:29], v70, s33, v[80:81]
	v_add_u32_e32 v74, 0x5088, v82
	v_add_u32_e32 v67, 0x7180, v66
	ds_read2_b32 v[68:69], v68 offset1:1
	ds_read2_b32 v[70:71], v71 offset1:1
	ds_read2_b32 v[72:73], v67 offset1:1
	ds_read2_b32 v[74:75], v74 offset1:1
	v_add_u32_e32 v67, 0x7188, v66
	ds_read_b32 v79, v80 offset:9664
	ds_read2_b32 v[76:77], v67 offset1:1
	s_waitcnt lgkmcnt(5)
	v_add_f32_e32 v67, v68, v78
	v_mul_f32_e32 v67, 0xbfb8aa3b, v67
	v_exp_f32_e32 v67, v67
	ds_read_b32 v68, v80 offset:9728
	s_waitcnt lgkmcnt(2)
	v_add_f32_e32 v70, v70, v79
	v_mul_f32_e32 v70, 0xbfb8aa3b, v70
	v_add_f32_e32 v67, 1.0, v67
	v_rcp_f32_e32 v67, v67
	v_exp_f32_e32 v70, v70
	v_mul_f32_e32 v67, 0xc1000000, v67
	s_waitcnt lgkmcnt(0)
	v_mul_f32_e32 v67, v68, v67
	v_mul_f32_e32 v67, 0x3fb8aa3b, v67
	v_exp_f32_e32 v67, v67
	v_add_f32_e32 v68, 1.0, v70
	v_rcp_f32_e32 v68, v68
	v_fma_f32 v70, -v67, v67, 1.0
	v_max_f32_e32 v70, 0, v70
	v_sqrt_f32_e32 v70, v70
	v_mul_f32_e32 v68, v72, v68
	v_mul_f32_e32 v68, v68, v70
	ds_write_b32 v66, v67 offset:9792
	ds_write_b32 v66, v68 offset:14144
	ds_read_b32 v67, v80 offset:9604
	ds_read_b32 v68, v80 offset:9668
	ds_read_b32 v70, v80 offset:9732
	s_waitcnt lgkmcnt(2)
	v_add_f32_e32 v67, v69, v67
	v_mul_f32_e32 v67, 0xbfb8aa3b, v67
	v_exp_f32_e32 v67, v67
	s_waitcnt lgkmcnt(1)
	v_add_f32_e32 v68, v71, v68
	v_mul_f32_e32 v68, 0xbfb8aa3b, v68
	v_exp_f32_e32 v68, v68
	v_add_f32_e32 v67, 1.0, v67
	v_rcp_f32_e32 v67, v67
	v_add_f32_e32 v68, 1.0, v68
	v_rcp_f32_e32 v68, v68
	v_mul_f32_e32 v67, 0xc1000000, v67
	s_waitcnt lgkmcnt(0)
	v_mul_f32_e32 v67, v70, v67
	v_mul_f32_e32 v67, 0x3fb8aa3b, v67
	v_exp_f32_e32 v67, v67
	v_mul_f32_e32 v68, v73, v68
	v_fma_f32 v69, -v67, v67, 1.0
	v_max_f32_e32 v69, 0, v69
	v_sqrt_f32_e32 v69, v69
	ds_write_b32 v66, v67 offset:9796
	v_mul_f32_e32 v67, v68, v69
	ds_write_b32 v66, v67 offset:14148
	ds_read_b32 v67, v80 offset:9608
	v_add_u32_e32 v68, 0x50c8, v82
	ds_read_b32 v70, v80 offset:9672
	ds_read_b32 v71, v80 offset:9736
	ds_read2_b32 v[68:69], v68 offset1:1
	s_waitcnt lgkmcnt(3)
	v_add_f32_e32 v67, v74, v67
	v_mul_f32_e32 v67, 0xbfb8aa3b, v67
	v_exp_f32_e32 v67, v67
	s_waitcnt lgkmcnt(0)
	v_add_f32_e32 v68, v68, v70
	v_mul_f32_e32 v68, 0xbfb8aa3b, v68
	v_exp_f32_e32 v68, v68
	v_add_f32_e32 v67, 1.0, v67
	v_rcp_f32_e32 v67, v67
	v_add_u32_e32 v74, 64, v230
	v_add_f32_e32 v68, 1.0, v68
	v_rcp_f32_e32 v68, v68
	v_mul_f32_e32 v67, 0xc1000000, v67
	v_mul_f32_e32 v67, v71, v67
	v_mul_f32_e32 v67, 0x3fb8aa3b, v67
	v_exp_f32_e32 v67, v67
	v_mul_f32_e32 v68, v76, v68
	v_add_u32_e32 v71, 0x3400, v240
	v_fma_f32 v70, -v67, v67, 1.0
	v_max_f32_e32 v70, 0, v70
	v_sqrt_f32_e32 v70, v70
	ds_write_b32 v66, v67 offset:9800
	v_mul_f32_e32 v67, v68, v70
	ds_write_b32 v66, v67 offset:14152
	ds_read_b32 v67, v80 offset:9612
	ds_read_b32 v68, v80 offset:9676
	ds_read_b32 v70, v80 offset:9740
	s_waitcnt lgkmcnt(2)
	v_add_f32_e32 v67, v75, v67
	v_mul_f32_e32 v67, 0xbfb8aa3b, v67
	v_exp_f32_e32 v67, v67
	s_waitcnt lgkmcnt(1)
	v_add_f32_e32 v68, v69, v68
	v_mul_f32_e32 v68, 0xbfb8aa3b, v68
	v_exp_f32_e32 v68, v68
	v_add_f32_e32 v67, 1.0, v67
	v_rcp_f32_e32 v67, v67
	v_add_f32_e32 v68, 1.0, v68
	v_rcp_f32_e32 v68, v68
	v_mul_f32_e32 v67, 0xc1000000, v67
	s_waitcnt lgkmcnt(0)
	v_mul_f32_e32 v67, v70, v67
	v_mul_f32_e32 v67, 0x3fb8aa3b, v67
	v_exp_f32_e32 v67, v67
	v_mul_f32_e32 v68, v77, v68
	v_add_u32_e32 v70, 0x2400, v240
	v_fma_f32 v69, -v67, v67, 1.0
	v_max_f32_e32 v69, 0, v69
	v_sqrt_f32_e32 v69, v69
	ds_write_b32 v66, v67 offset:9804
	v_mul_f32_e32 v67, v68, v69
	ds_write_b32 v66, v67 offset:14156
	s_waitcnt lgkmcnt(0)
	s_barrier
	ds_read2_b32 v[72:73], v70 offset0:144 offset1:161
	ds_read2_b32 v[68:69], v71 offset0:208 offset1:225
	v_add_u32_e32 v66, 0x3600, v240
	ds_read2_b32 v[70:71], v70 offset0:178 offset1:195
	ds_read2_b32 v[66:67], v66 offset0:114 offset1:131
	s_waitcnt lgkmcnt(3)
	v_mul_f32_e32 v76, v72, v73
	s_waitcnt lgkmcnt(2)
	v_fma_f32 v75, 0, v72, v68
	v_fma_f32 v75, v75, v73, v69
	s_waitcnt lgkmcnt(1)
	v_mul_f32_e32 v76, v76, v70
	s_waitcnt lgkmcnt(0)
	v_fma_f32 v75, v75, v70, v66
	v_mul_f32_e32 v76, v76, v71
	v_fma_f32 v75, v75, v71, v67
	ds_write2st64_b32 v74, v76, v75 offset0:72 offset1:76
	s_waitcnt lgkmcnt(0)
	s_barrier
	ds_read_b32 v74, v239 offset:20544
	ds_read2st64_b32 v[80:81], v241 offset1:4
	v_add_u32_e32 v76, 64, v241
	ds_read2st64_b32 v[82:83], v76 offset1:4
	v_add_u32_e32 v75, 128, v241
	ds_read2st64_b32 v[84:85], v75 offset1:4
	v_add_u32_e32 v76, 192, v241
	ds_read2st64_b32 v[86:87], v76 offset1:4
	v_add_u32_e32 v75, 256, v241
	ds_read2st64_b32 v[88:89], v75 offset1:4
	v_add_u32_e32 v76, 320, v241
	ds_read2st64_b32 v[90:91], v76 offset1:4
	v_add_u32_e32 v75, 384, v241
	ds_read2st64_b32 v[92:93], v75 offset1:4
	v_add_u32_e32 v76, 448, v241
	ds_read2st64_b32 v[94:95], v76 offset1:4
	v_add_u32_e32 v75, 512, v241
	ds_read2st64_b32 v[96:97], v75 offset1:4
	v_add_u32_e32 v76, 576, v241
	ds_read2st64_b32 v[98:99], v76 offset1:4
	s_waitcnt lgkmcnt(6)
	v_add_u32_e32 v75, 640, v241
	ds_read2st64_b32 v[100:101], v75 offset1:4
	v_add_u32_e32 v76, 704, v241
	ds_read2st64_b32 v[102:103], v76 offset1:4
	v_add_u32_e32 v75, 768, v241
	ds_read2st64_b32 v[104:105], v75 offset1:4
	v_add_u32_e32 v76, 832, v241
	ds_read2st64_b32 v[106:107], v76 offset1:4
	v_add_u32_e32 v75, 896, v241
	ds_read2st64_b32 v[108:109], v75 offset1:4
	s_mov_b64 s[28:29], exec
	s_waitcnt lgkmcnt(0)
	v_cmpx_lt_u32_e32 vcc, 0, v233
	v_fma_f32 v74, v80, v74, v81
	v_cmpx_lt_u32_e32 vcc, 1, v233
	v_fma_f32 v74, v82, v74, v83
	v_cmpx_lt_u32_e32 vcc, 2, v233
	v_fma_f32 v74, v84, v74, v85
	v_cmpx_lt_u32_e32 vcc, 3, v233
	v_fma_f32 v74, v86, v74, v87
	v_cmpx_lt_u32_e32 vcc, 4, v233
	v_fma_f32 v74, v88, v74, v89
	v_cmpx_lt_u32_e32 vcc, 5, v233
	v_fma_f32 v74, v90, v74, v91
	v_cmpx_lt_u32_e32 vcc, 6, v233
	v_fma_f32 v74, v92, v74, v93
	v_cmpx_lt_u32_e32 vcc, 7, v233
	v_fma_f32 v74, v94, v74, v95
	v_cmpx_lt_u32_e32 vcc, 8, v233
	v_fma_f32 v74, v96, v74, v97
	v_cmpx_lt_u32_e32 vcc, 9, v233
	v_fma_f32 v74, v98, v74, v99
	v_cmpx_lt_u32_e32 vcc, 10, v233
	v_fma_f32 v74, v100, v74, v101
	v_cmpx_lt_u32_e32 vcc, 11, v233
	v_fma_f32 v74, v102, v74, v103
	v_cmpx_lt_u32_e32 vcc, 12, v233
	v_fma_f32 v74, v104, v74, v105
	v_cmpx_lt_u32_e32 vcc, 13, v233
	v_fma_f32 v74, v106, v74, v107
	v_cmpx_lt_u32_e32 vcc, 14, v233
	v_fma_f32 v74, v108, v74, v109
	s_mov_b64 exec, s[28:29]

.LBB0_612:
	ds_read_b128 v[162:165], v130
	ds_read_b128 v[166:169], v158 offset:36864
	ds_read_b128 v[170:173], v130 offset:32
	ds_read_b128 v[174:177], v158 offset:36896
	ds_read_b128 v[178:181], v158 offset:41472
	ds_read_b128 v[182:185], v158 offset:41504
	s_cmp_gt_u32 s20, 60
	s_waitcnt lgkmcnt(4)
	v_mfma_f32_32x32x16_bf16 v[48:63], v[162:165], v[166:169], v[48:63]
	s_waitcnt lgkmcnt(1)
	v_mfma_f32_32x32x16_bf16 v[32:47], v[162:165], v[178:181], v[32:47]
	ds_read_b128 v[162:165], v130 offset:4608
	ds_read_b128 v[186:189], v130 offset:4640
	s_waitcnt lgkmcnt(1)
	v_mfma_f32_32x32x16_bf16 v[16:31], v[162:165], v[166:169], v[16:31]
	v_mfma_f32_32x32x16_bf16 v[0:15], v[162:165], v[178:181], v[0:15]
	v_mfma_f32_32x32x16_bf16 v[48:63], v[170:173], v[174:177], v[48:63]
	v_mfma_f32_32x32x16_bf16 v[32:47], v[170:173], v[182:185], v[32:47]
	s_waitcnt lgkmcnt(0)
	v_mfma_f32_32x32x16_bf16 v[16:31], v[186:189], v[174:177], v[16:31]
	ds_read_b128 v[162:165], v130 offset:64
	ds_read_b128 v[166:169], v158 offset:36928
	ds_read_b128 v[170:173], v130 offset:96
	ds_read_b128 v[174:177], v158 offset:36960
	v_mfma_f32_32x32x16_bf16 v[0:15], v[186:189], v[182:185], v[0:15]
	ds_read_b128 v[178:181], v158 offset:41536
	ds_read_b128 v[182:185], v158 offset:41568
	s_waitcnt lgkmcnt(4)
	v_mfma_f32_32x32x16_bf16 v[48:63], v[162:165], v[166:169], v[48:63]
	s_waitcnt lgkmcnt(1)
	v_mfma_f32_32x32x16_bf16 v[32:47], v[162:165], v[178:181], v[32:47]
	ds_read_b128 v[162:165], v130 offset:4672
	ds_read_b128 v[186:189], v130 offset:4704
	s_mov_b64 vcc, s[4:5]
	s_cbranch_vccnz .Lk10_last
	s_waitcnt vmcnt(8)
	ds_write_b128 v143, v[76:79] offset:18432
	ds_write_b128 v143, v[84:87] offset:23040
	ds_write_b128 v143, v[96:99] offset:27648
	ds_write_b128 v143, v[100:103] offset:32256
	ds_write_b128 v143, v[104:107] offset:55296
	ds_write_b128 v143, v[112:115] offset:59904
	ds_write_b128 v143, v[120:123] offset:64512
	ds_write_b128 v145, v[124:127] offset:32256
	s_branch .Lk10_join
.Lk10_last:
	s_waitcnt vmcnt(0)
	ds_write_b128 v143, v[76:79] offset:18432
	ds_write_b128 v143, v[84:87] offset:23040
	ds_write_b128 v143, v[96:99] offset:27648
	ds_write_b128 v143, v[100:103] offset:32256
	ds_write_b128 v143, v[104:107] offset:55296
	ds_write_b128 v143, v[112:115] offset:59904
	ds_write_b128 v143, v[120:123] offset:64512
	ds_write_b128 v145, v[124:127] offset:32256
.Lk10_join:
	s_waitcnt lgkmcnt(0)
	s_barrier
	v_mfma_f32_32x32x16_bf16 v[16:31], v[162:165], v[166:169], v[16:31]
	v_mfma_f32_32x32x16_bf16 v[0:15], v[162:165], v[178:181], v[0:15]
	v_mfma_f32_32x32x16_bf16 v[48:63], v[170:173], v[174:177], v[48:63]
	v_mfma_f32_32x32x16_bf16 v[32:47], v[170:173], v[182:185], v[32:47]
	v_mfma_f32_32x32x16_bf16 v[16:31], v[186:189], v[174:177], v[16:31]
	v_mfma_f32_32x32x16_bf16 v[0:15], v[186:189], v[182:185], v[0:15]
	s_cbranch_scc1 .LBB0_614
	v_add_co_u32_e32 v76, vcc, 0xb6c0000, v156
	s_nop 1
	v_addc_co_u32_e32 v77, vcc, 0, v157, vcc
	v_add_co_u32_e32 v84, vcc, 0xb700000, v156
	s_nop 1
	v_addc_co_u32_e32 v85, vcc, 0, v157, vcc
	v_add_co_u32_e32 v96, vcc, 0xb740000, v156
	global_load_dwordx4 v[76:79], v[76:77], off offset:640
	s_nop 0
	global_load_dwordx4 v[84:87], v[84:85], off offset:640
	v_addc_co_u32_e32 v97, vcc, 0, v157, vcc
	v_add_co_u32_e32 v100, vcc, 0xb780000, v156
	s_nop 1
	v_addc_co_u32_e32 v101, vcc, 0, v157, vcc
	v_add_co_u32_e32 v104, vcc, 0x2640000, v154
	global_load_dwordx4 v[96:99], v[96:97], off offset:640
	s_nop 0
	global_load_dwordx4 v[100:103], v[100:101], off offset:640
	v_addc_co_u32_e32 v105, vcc, 0, v155, vcc
	v_add_co_u32_e32 v112, vcc, 0x2680000, v154
	s_nop 1
	v_addc_co_u32_e32 v113, vcc, 0, v155, vcc
	v_add_co_u32_e32 v120, vcc, 0x26c0000, v154
	global_load_dwordx4 v[104:107], v[104:105], off offset:384
	s_nop 0
	global_load_dwordx4 v[112:115], v[112:113], off offset:384
	v_addc_co_u32_e32 v121, vcc, 0, v155, vcc
	v_add_co_u32_e32 v124, vcc, 0x2700000, v154
	s_nop 1
	v_addc_co_u32_e32 v125, vcc, 0, v155, vcc
	global_load_dwordx4 v[120:123], v[120:121], off offset:384
	s_nop 0
	global_load_dwordx4 v[124:127], v[124:125], off offset:384
.LBB0_614:
	ds_read_b128 v[154:157], v130 offset:18432
	ds_read_b128 v[162:165], v158 offset:55296
	ds_read_b128 v[166:169], v130 offset:18464
	ds_read_b128 v[170:173], v158 offset:55328
	ds_read_b128 v[174:177], v158 offset:59904
	ds_read_b128 v[178:181], v158 offset:59936
	s_andn2_b64 vcc, exec, s[6:7]
	s_waitcnt lgkmcnt(4)
	v_mfma_f32_32x32x16_bf16 v[48:63], v[154:157], v[162:165], v[48:63]
	s_waitcnt lgkmcnt(1)
	v_mfma_f32_32x32x16_bf16 v[32:47], v[154:157], v[174:177], v[32:47]
	ds_read_b128 v[154:157], v130 offset:23040
	ds_read_b128 v[182:185], v130 offset:23072
	s_waitcnt lgkmcnt(1)
	v_mfma_f32_32x32x16_bf16 v[16:31], v[154:157], v[162:165], v[16:31]
	v_mfma_f32_32x32x16_bf16 v[0:15], v[154:157], v[174:177], v[0:15]
	v_mfma_f32_32x32x16_bf16 v[48:63], v[166:169], v[170:173], v[48:63]
	v_mfma_f32_32x32x16_bf16 v[32:47], v[166:169], v[178:181], v[32:47]
	s_waitcnt lgkmcnt(0)
	v_mfma_f32_32x32x16_bf16 v[16:31], v[182:185], v[170:173], v[16:31]
	ds_read_b128 v[154:157], v130 offset:18496
	ds_read_b128 v[162:165], v158 offset:55360
	ds_read_b128 v[166:169], v130 offset:18528
	ds_read_b128 v[170:173], v158 offset:55392
	v_mfma_f32_32x32x16_bf16 v[0:15], v[182:185], v[178:181], v[0:15]
	ds_read_b128 v[174:177], v158 offset:59968
	ds_read_b128 v[178:181], v158 offset:60000
	s_waitcnt lgkmcnt(4)
	v_mfma_f32_32x32x16_bf16 v[48:63], v[154:157], v[162:165], v[48:63]
	s_waitcnt lgkmcnt(1)
	v_mfma_f32_32x32x16_bf16 v[32:47], v[154:157], v[174:177], v[32:47]
	ds_read_b128 v[154:157], v130 offset:23104
	ds_read_b128 v[182:185], v130 offset:23136
	s_waitcnt lgkmcnt(1)
	v_mfma_f32_32x32x16_bf16 v[16:31], v[154:157], v[162:165], v[16:31]
	v_mfma_f32_32x32x16_bf16 v[0:15], v[154:157], v[174:177], v[0:15]
	v_mfma_f32_32x32x16_bf16 v[48:63], v[166:169], v[170:173], v[48:63]
	v_mfma_f32_32x32x16_bf16 v[32:47], v[166:169], v[178:181], v[32:47]
	s_waitcnt lgkmcnt(0)
	v_mfma_f32_32x32x16_bf16 v[16:31], v[182:185], v[170:173], v[16:31]
	v_mfma_f32_32x32x16_bf16 v[0:15], v[182:185], v[178:181], v[0:15]
	s_cbranch_vccnz .LBB0_609
	s_waitcnt vmcnt(8)
	ds_write_b128 v143, v[64:67]
	ds_write_b128 v143, v[68:71] offset:4608
	ds_write_b128 v143, v[72:75] offset:9216
	ds_write_b128 v143, v[88:91] offset:13824
	ds_write_b128 v143, v[80:83] offset:36864
	ds_write_b128 v143, v[92:95] offset:41472
	ds_write_b128 v143, v[108:111] offset:46080
	ds_write_b128 v143, v[116:119] offset:50688
	s_branch .LBB0_609
